# P8 expert tail: ids and the first group's 32 gathers are issued at the start of the tail (behind the row/scale loads) and land while the row is quantized
# speedup vs baseline: 1.0044x; 1.0044x over previous
.LBB0_926:
	s_waitcnt lgkmcnt(0)
	v_and_b32_e32 v0, 63, v204
	v_lshlrev_b32_e32 v1, 12, v4
	v_lshl_add_u32 v1, v0, 5, v1
	v_add_u32_e32 v1, 0x13288000, v1
	global_load_dwordx4 v[216:219], v1, s[94:95]
	global_load_dwordx4 v[220:223], v1, s[94:95] offset:16
	global_load_dwordx4 v[224:227], v1, s[94:95] offset:2048
	global_load_dwordx4 v[228:231], v1, s[94:95] offset:2064
	ds_read_b32 v232, v170
	ds_read_b32 v233, v170 offset:256
	ds_read_b32 v234, v170 offset:512
	ds_read_b32 v235, v170 offset:768
	v_lshlrev_b32_e32 v28, 3, v0
	v_add_u32_e32 v29, 0x4008000, v28
	v_add_u32_e32 v28, 0x8000, v28
	s_waitcnt lgkmcnt(0)
	v_lshlrev_b32_e32 v2, 2, v232
	v_lshlrev_b32_e32 v3, 2, v233
	global_load_dword v236, v2, s[74:75]
	global_load_dword v237, v3, s[74:75]
	global_load_dword v238, v2, s[76:77]
	global_load_dword v239, v3, s[76:77]
	v_mov_b32_e32 v32, 0
	v_mov_b32_e32 v33, 0
	v_mov_b32_e32 v34, 0
	v_mov_b32_e32 v35, 0
	v_mov_b32_e32 v36, 0
	v_mov_b32_e32 v37, 0
	v_mov_b32_e32 v38, 0
	v_mov_b32_e32 v39, 0
	v_mov_b32_e32 v40, 0
	v_mov_b32_e32 v41, 0
	v_mov_b32_e32 v42, 0
	v_mov_b32_e32 v43, 0
	v_mov_b32_e32 v44, 0
	v_mov_b32_e32 v45, 0
	v_mov_b32_e32 v46, 0
	v_mov_b32_e32 v47, 0
	v_mov_b32_e32 v48, 0
	v_mov_b32_e32 v49, 0
	v_mov_b32_e32 v50, 0
	v_mov_b32_e32 v51, 0
	v_mov_b32_e32 v52, 0
	v_mov_b32_e32 v53, 0
	v_mov_b32_e32 v54, 0
	v_mov_b32_e32 v55, 0
	v_mov_b32_e32 v56, 0
	v_mov_b32_e32 v57, 0
	v_mov_b32_e32 v58, 0
	v_mov_b32_e32 v59, 0
	v_mov_b32_e32 v60, 0
	v_mov_b32_e32 v61, 0
	v_mov_b32_e32 v62, 0
	v_mov_b32_e32 v63, 0
	v_lshlrev_b32_e32 v2, 2, v0
	v_sub_u32_e32 v25, v170, v2
	v_add_u32_e32 v5, 0x1000, v170
	v_lshrrev_b32_e32 v2, 4, v0
	v_lshrrev_b32_e32 v3, 5, v0
	v_and_b32_e32 v2, 1, v2
	v_lshl_or_b32 v2, v2, 1, v3
	v_add_u32_e32 v3, 0x1000, v25
	v_lshl_add_u32 v26, v2, 2, v3
	v_add_u32_e32 v27, 16, v26
	ds_read_b128 v[10:13], v25
	ds_read_b128 v[18:21], v25 offset:16
	v_add_u32_e32 v25, 32, v25
	s_waitcnt lgkmcnt(0)
	v_readfirstlane_b32 s33, v10
	s_lshl_b32 s33, s33, 10
	s_add_u32 s72, s94, s33
	s_addc_u32 s73, s95, 0
	global_load_dwordx2 v[64:65], v28, s[72:73]
	global_load_dwordx2 v[66:67], v28, s[72:73] offset:512
	global_load_dwordx2 v[96:97], v29, s[72:73]
	global_load_dwordx2 v[98:99], v29, s[72:73] offset:512
	v_readfirstlane_b32 s33, v11
	s_lshl_b32 s33, s33, 10
	s_add_u32 s72, s94, s33
	s_addc_u32 s73, s95, 0
	global_load_dwordx2 v[68:69], v28, s[72:73]
	global_load_dwordx2 v[70:71], v28, s[72:73] offset:512
	global_load_dwordx2 v[100:101], v29, s[72:73]
	global_load_dwordx2 v[102:103], v29, s[72:73] offset:512
	v_readfirstlane_b32 s33, v12
	s_lshl_b32 s33, s33, 10
	s_add_u32 s72, s94, s33
	s_addc_u32 s73, s95, 0
	global_load_dwordx2 v[72:73], v28, s[72:73]
	global_load_dwordx2 v[74:75], v28, s[72:73] offset:512
	global_load_dwordx2 v[104:105], v29, s[72:73]
	global_load_dwordx2 v[106:107], v29, s[72:73] offset:512
	v_readfirstlane_b32 s33, v13
	s_lshl_b32 s33, s33, 10
	s_add_u32 s72, s94, s33
	s_addc_u32 s73, s95, 0
	global_load_dwordx2 v[76:77], v28, s[72:73]
	global_load_dwordx2 v[78:79], v28, s[72:73] offset:512
	global_load_dwordx2 v[108:109], v29, s[72:73]
	global_load_dwordx2 v[110:111], v29, s[72:73] offset:512
	v_readfirstlane_b32 s33, v18
	s_lshl_b32 s33, s33, 10
	s_add_u32 s72, s94, s33
	s_addc_u32 s73, s95, 0
	global_load_dwordx2 v[80:81], v28, s[72:73]
	global_load_dwordx2 v[82:83], v28, s[72:73] offset:512
	global_load_dwordx2 v[112:113], v29, s[72:73]
	global_load_dwordx2 v[114:115], v29, s[72:73] offset:512
	v_readfirstlane_b32 s33, v19
	s_lshl_b32 s33, s33, 10
	s_add_u32 s72, s94, s33
	s_addc_u32 s73, s95, 0
	global_load_dwordx2 v[84:85], v28, s[72:73]
	global_load_dwordx2 v[86:87], v28, s[72:73] offset:512
	global_load_dwordx2 v[116:117], v29, s[72:73]
	global_load_dwordx2 v[118:119], v29, s[72:73] offset:512
	v_readfirstlane_b32 s33, v20
	s_lshl_b32 s33, s33, 10
	s_add_u32 s72, s94, s33
	s_addc_u32 s73, s95, 0
	global_load_dwordx2 v[88:89], v28, s[72:73]
	global_load_dwordx2 v[90:91], v28, s[72:73] offset:512
	global_load_dwordx2 v[120:121], v29, s[72:73]
	global_load_dwordx2 v[122:123], v29, s[72:73] offset:512
	v_readfirstlane_b32 s33, v21
	s_lshl_b32 s33, s33, 10
	s_add_u32 s72, s94, s33
	s_addc_u32 s73, s95, 0
	global_load_dwordx2 v[92:93], v28, s[72:73]
	global_load_dwordx2 v[94:95], v28, s[72:73] offset:512
	global_load_dwordx2 v[124:125], v29, s[72:73]
	global_load_dwordx2 v[126:127], v29, s[72:73] offset:512
	s_waitcnt vmcnt(36)
	v_lshlrev_b32_e32 v128, 16, v216
	v_and_b32_e32 v129, 0xffff0000, v216
	v_lshlrev_b32_e32 v130, 16, v217
	v_and_b32_e32 v131, 0xffff0000, v217
	v_lshlrev_b32_e32 v132, 16, v218
	v_and_b32_e32 v133, 0xffff0000, v218
	v_lshlrev_b32_e32 v134, 16, v219
	v_and_b32_e32 v135, 0xffff0000, v219
	v_lshlrev_b32_e32 v136, 16, v220
	v_and_b32_e32 v137, 0xffff0000, v220
	v_lshlrev_b32_e32 v138, 16, v221
	v_and_b32_e32 v139, 0xffff0000, v221
	v_lshlrev_b32_e32 v140, 16, v222
	v_and_b32_e32 v141, 0xffff0000, v222
	v_lshlrev_b32_e32 v142, 16, v223
	v_and_b32_e32 v143, 0xffff0000, v223
	v_lshlrev_b32_e32 v144, 16, v224
	v_and_b32_e32 v145, 0xffff0000, v224
	v_lshlrev_b32_e32 v146, 16, v225
	v_and_b32_e32 v147, 0xffff0000, v225
	v_lshlrev_b32_e32 v148, 16, v226
	v_and_b32_e32 v149, 0xffff0000, v226
	v_lshlrev_b32_e32 v150, 16, v227
	v_and_b32_e32 v151, 0xffff0000, v227
	v_lshlrev_b32_e32 v152, 16, v228
	v_and_b32_e32 v153, 0xffff0000, v228
	v_lshlrev_b32_e32 v154, 16, v229
	v_and_b32_e32 v155, 0xffff0000, v229
	v_lshlrev_b32_e32 v156, 16, v230
	v_and_b32_e32 v157, 0xffff0000, v230
	v_lshlrev_b32_e32 v158, 16, v231
	v_and_b32_e32 v159, 0xffff0000, v231
	v_max3_f32 v6, |v128|, |v129|, |v130|
	v_max3_f32 v6, v6, |v131|, |v132|
	v_max3_f32 v6, v6, |v133|, |v134|
	v_max3_f32 v6, v6, |v135|, |v136|
	v_max3_f32 v6, v6, |v137|, |v138|
	v_max3_f32 v6, v6, |v139|, |v140|
	v_max3_f32 v6, v6, |v141|, |v142|
	v_max3_f32 v6, v6, |v143|, |v144|
	v_max3_f32 v6, v6, |v145|, |v146|
	v_max3_f32 v6, v6, |v147|, |v148|
	v_max3_f32 v6, v6, |v149|, |v150|
	v_max3_f32 v6, v6, |v151|, |v152|
	v_max3_f32 v6, v6, |v153|, |v154|
	v_max3_f32 v6, v6, |v155|, |v156|
	v_max3_f32 v6, v6, |v157|, |v158|
	v_max_f32_e64 v6, v6, |v159|
	v_mov_b32_e32 v2, v6
	v_mov_b32_e32 v3, v6
	s_nop 1
	v_permlane32_swap_b32_e32 v2, v3
	v_max_f32_e32 v6, v2, v3
	v_mov_b32_e32 v2, v6
	v_mov_b32_e32 v3, v6
	s_nop 1
	v_permlane16_swap_b32_e32 v2, v3
	v_max_f32_e32 v6, v2, v3
	s_nop 1
	v_max_f32_dpp v6, v6, v6 row_ror:8 row_mask:0xf bank_mask:0xf
	s_nop 1
	v_max_f32_dpp v6, v6, v6 row_ror:4 row_mask:0xf bank_mask:0xf
	s_nop 1
	v_max_f32_dpp v6, v6, v6 row_ror:2 row_mask:0xf bank_mask:0xf
	s_nop 1
	v_max_f32_dpp v6, v6, v6 row_ror:1 row_mask:0xf bank_mask:0xf
	v_mul_f32_e32 v7, 0x3e124925, v6
	v_cmp_lt_f32_e32 vcc, 0, v6
	s_nop 1
	v_cndmask_b32_e32 v7, 1.0, v7, vcc
	v_mul_f32_e32 v10, 0x3d924925, v7
	v_rcp_f32_e32 v11, v7
	v_rcp_f32_e32 v12, v10
	s_mov_b32 s33, 0xc0e00000
	v_mov_b32_e32 v13, 0x40e00000
	v_mul_f32_e32 v21, v128, v11
	v_rndne_f32_e32 v21, v21
	v_med3_f32 v21, v21, s33, v13
	v_fma_f32 v22, -v7, v21, v128
	v_mul_f32_e32 v22, v22, v12
	v_rndne_f32_e32 v22, v22
	v_med3_f32 v22, v22, s33, v13
	v_cvt_i32_f32_e32 v21, v21
	v_cvt_i32_f32_e32 v22, v22
	v_and_b32_e32 v208, 15, v21
	v_and_b32_e32 v212, 15, v22
	v_mul_f32_e32 v23, v129, v11
	v_rndne_f32_e32 v23, v23
	v_med3_f32 v23, v23, s33, v13
	v_fma_f32 v30, -v7, v23, v129
	v_mul_f32_e32 v30, v30, v12
	v_rndne_f32_e32 v30, v30
	v_med3_f32 v30, v30, s33, v13
	v_cvt_i32_f32_e32 v23, v23
	v_cvt_i32_f32_e32 v30, v30
	v_and_b32_e32 v23, 15, v23
	v_and_b32_e32 v30, 15, v30
	v_lshl_or_b32 v208, v23, 4, v208
	v_lshl_or_b32 v212, v30, 4, v212
	v_mul_f32_e32 v21, v130, v11
	v_rndne_f32_e32 v21, v21
	v_med3_f32 v21, v21, s33, v13
	v_fma_f32 v22, -v7, v21, v130
	v_mul_f32_e32 v22, v22, v12
	v_rndne_f32_e32 v22, v22
	v_med3_f32 v22, v22, s33, v13
	v_cvt_i32_f32_e32 v21, v21
	v_cvt_i32_f32_e32 v22, v22
	v_and_b32_e32 v21, 15, v21
	v_and_b32_e32 v22, 15, v22
	v_lshl_or_b32 v208, v21, 8, v208
	v_lshl_or_b32 v212, v22, 8, v212
	v_mul_f32_e32 v23, v131, v11
	v_rndne_f32_e32 v23, v23
	v_med3_f32 v23, v23, s33, v13
	v_fma_f32 v30, -v7, v23, v131
	v_mul_f32_e32 v30, v30, v12
	v_rndne_f32_e32 v30, v30
	v_med3_f32 v30, v30, s33, v13
	v_cvt_i32_f32_e32 v23, v23
	v_cvt_i32_f32_e32 v30, v30
	v_and_b32_e32 v23, 15, v23
	v_and_b32_e32 v30, 15, v30
	v_lshl_or_b32 v208, v23, 12, v208
	v_lshl_or_b32 v212, v30, 12, v212
	v_mul_f32_e32 v21, v132, v11
	v_rndne_f32_e32 v21, v21
	v_med3_f32 v21, v21, s33, v13
	v_fma_f32 v22, -v7, v21, v132
	v_mul_f32_e32 v22, v22, v12
	v_rndne_f32_e32 v22, v22
	v_med3_f32 v22, v22, s33, v13
	v_cvt_i32_f32_e32 v21, v21
	v_cvt_i32_f32_e32 v22, v22
	v_and_b32_e32 v21, 15, v21
	v_and_b32_e32 v22, 15, v22
	v_lshl_or_b32 v208, v21, 16, v208
	v_lshl_or_b32 v212, v22, 16, v212
	v_mul_f32_e32 v23, v133, v11
	v_rndne_f32_e32 v23, v23
	v_med3_f32 v23, v23, s33, v13
	v_fma_f32 v30, -v7, v23, v133
	v_mul_f32_e32 v30, v30, v12
	v_rndne_f32_e32 v30, v30
	v_med3_f32 v30, v30, s33, v13
	v_cvt_i32_f32_e32 v23, v23
	v_cvt_i32_f32_e32 v30, v30
	v_and_b32_e32 v23, 15, v23
	v_and_b32_e32 v30, 15, v30
	v_lshl_or_b32 v208, v23, 20, v208
	v_lshl_or_b32 v212, v30, 20, v212
	v_mul_f32_e32 v21, v134, v11
	v_rndne_f32_e32 v21, v21
	v_med3_f32 v21, v21, s33, v13
	v_fma_f32 v22, -v7, v21, v134
	v_mul_f32_e32 v22, v22, v12
	v_rndne_f32_e32 v22, v22
	v_med3_f32 v22, v22, s33, v13
	v_cvt_i32_f32_e32 v21, v21
	v_cvt_i32_f32_e32 v22, v22
	v_and_b32_e32 v21, 15, v21
	v_and_b32_e32 v22, 15, v22
	v_lshl_or_b32 v208, v21, 24, v208
	v_lshl_or_b32 v212, v22, 24, v212
	v_mul_f32_e32 v23, v135, v11
	v_rndne_f32_e32 v23, v23
	v_med3_f32 v23, v23, s33, v13
	v_fma_f32 v30, -v7, v23, v135
	v_mul_f32_e32 v30, v30, v12
	v_rndne_f32_e32 v30, v30
	v_med3_f32 v30, v30, s33, v13
	v_cvt_i32_f32_e32 v23, v23
	v_cvt_i32_f32_e32 v30, v30
	v_lshl_or_b32 v208, v23, 28, v208
	v_lshl_or_b32 v212, v30, 28, v212
	v_mul_f32_e32 v21, v136, v11
	v_rndne_f32_e32 v21, v21
	v_med3_f32 v21, v21, s33, v13
	v_fma_f32 v22, -v7, v21, v136
	v_mul_f32_e32 v22, v22, v12
	v_rndne_f32_e32 v22, v22
	v_med3_f32 v22, v22, s33, v13
	v_cvt_i32_f32_e32 v21, v21
	v_cvt_i32_f32_e32 v22, v22
	v_and_b32_e32 v209, 15, v21
	v_and_b32_e32 v213, 15, v22
	v_mul_f32_e32 v23, v137, v11
	v_rndne_f32_e32 v23, v23
	v_med3_f32 v23, v23, s33, v13
	v_fma_f32 v30, -v7, v23, v137
	v_mul_f32_e32 v30, v30, v12
	v_rndne_f32_e32 v30, v30
	v_med3_f32 v30, v30, s33, v13
	v_cvt_i32_f32_e32 v23, v23
	v_cvt_i32_f32_e32 v30, v30
	v_and_b32_e32 v23, 15, v23
	v_and_b32_e32 v30, 15, v30
	v_lshl_or_b32 v209, v23, 4, v209
	v_lshl_or_b32 v213, v30, 4, v213
	v_mul_f32_e32 v21, v138, v11
	v_rndne_f32_e32 v21, v21
	v_med3_f32 v21, v21, s33, v13
	v_fma_f32 v22, -v7, v21, v138
	v_mul_f32_e32 v22, v22, v12
	v_rndne_f32_e32 v22, v22
	v_med3_f32 v22, v22, s33, v13
	v_cvt_i32_f32_e32 v21, v21
	v_cvt_i32_f32_e32 v22, v22
	v_and_b32_e32 v21, 15, v21
	v_and_b32_e32 v22, 15, v22
	v_lshl_or_b32 v209, v21, 8, v209
	v_lshl_or_b32 v213, v22, 8, v213
	v_mul_f32_e32 v23, v139, v11
	v_rndne_f32_e32 v23, v23
	v_med3_f32 v23, v23, s33, v13
	v_fma_f32 v30, -v7, v23, v139
	v_mul_f32_e32 v30, v30, v12
	v_rndne_f32_e32 v30, v30
	v_med3_f32 v30, v30, s33, v13
	v_cvt_i32_f32_e32 v23, v23
	v_cvt_i32_f32_e32 v30, v30
	v_and_b32_e32 v23, 15, v23
	v_and_b32_e32 v30, 15, v30
	v_lshl_or_b32 v209, v23, 12, v209
	v_lshl_or_b32 v213, v30, 12, v213
	v_mul_f32_e32 v21, v140, v11
	v_rndne_f32_e32 v21, v21
	v_med3_f32 v21, v21, s33, v13
	v_fma_f32 v22, -v7, v21, v140
	v_mul_f32_e32 v22, v22, v12
	v_rndne_f32_e32 v22, v22
	v_med3_f32 v22, v22, s33, v13
	v_cvt_i32_f32_e32 v21, v21
	v_cvt_i32_f32_e32 v22, v22
	v_and_b32_e32 v21, 15, v21
	v_and_b32_e32 v22, 15, v22
	v_lshl_or_b32 v209, v21, 16, v209
	v_lshl_or_b32 v213, v22, 16, v213
	v_mul_f32_e32 v23, v141, v11
	v_rndne_f32_e32 v23, v23
	v_med3_f32 v23, v23, s33, v13
	v_fma_f32 v30, -v7, v23, v141
	v_mul_f32_e32 v30, v30, v12
	v_rndne_f32_e32 v30, v30
	v_med3_f32 v30, v30, s33, v13
	v_cvt_i32_f32_e32 v23, v23
	v_cvt_i32_f32_e32 v30, v30
	v_and_b32_e32 v23, 15, v23
	v_and_b32_e32 v30, 15, v30
	v_lshl_or_b32 v209, v23, 20, v209
	v_lshl_or_b32 v213, v30, 20, v213
	v_mul_f32_e32 v21, v142, v11
	v_rndne_f32_e32 v21, v21
	v_med3_f32 v21, v21, s33, v13
	v_fma_f32 v22, -v7, v21, v142
	v_mul_f32_e32 v22, v22, v12
	v_rndne_f32_e32 v22, v22
	v_med3_f32 v22, v22, s33, v13
	v_cvt_i32_f32_e32 v21, v21
	v_cvt_i32_f32_e32 v22, v22
	v_and_b32_e32 v21, 15, v21
	v_and_b32_e32 v22, 15, v22
	v_lshl_or_b32 v209, v21, 24, v209
	v_lshl_or_b32 v213, v22, 24, v213
	v_mul_f32_e32 v23, v143, v11
	v_rndne_f32_e32 v23, v23
	v_med3_f32 v23, v23, s33, v13
	v_fma_f32 v30, -v7, v23, v143
	v_mul_f32_e32 v30, v30, v12
	v_rndne_f32_e32 v30, v30
	v_med3_f32 v30, v30, s33, v13
	v_cvt_i32_f32_e32 v23, v23
	v_cvt_i32_f32_e32 v30, v30
	v_lshl_or_b32 v209, v23, 28, v209
	v_lshl_or_b32 v213, v30, 28, v213
	v_mul_f32_e32 v21, v144, v11
	v_rndne_f32_e32 v21, v21
	v_med3_f32 v21, v21, s33, v13
	v_fma_f32 v22, -v7, v21, v144
	v_mul_f32_e32 v22, v22, v12
	v_rndne_f32_e32 v22, v22
	v_med3_f32 v22, v22, s33, v13
	v_cvt_i32_f32_e32 v21, v21
	v_cvt_i32_f32_e32 v22, v22
	v_and_b32_e32 v210, 15, v21
	v_and_b32_e32 v214, 15, v22
	v_mul_f32_e32 v23, v145, v11
	v_rndne_f32_e32 v23, v23
	v_med3_f32 v23, v23, s33, v13
	v_fma_f32 v30, -v7, v23, v145
	v_mul_f32_e32 v30, v30, v12
	v_rndne_f32_e32 v30, v30
	v_med3_f32 v30, v30, s33, v13
	v_cvt_i32_f32_e32 v23, v23
	v_cvt_i32_f32_e32 v30, v30
	v_and_b32_e32 v23, 15, v23
	v_and_b32_e32 v30, 15, v30
	v_lshl_or_b32 v210, v23, 4, v210
	v_lshl_or_b32 v214, v30, 4, v214
	v_mul_f32_e32 v21, v146, v11
	v_rndne_f32_e32 v21, v21
	v_med3_f32 v21, v21, s33, v13
	v_fma_f32 v22, -v7, v21, v146
	v_mul_f32_e32 v22, v22, v12
	v_rndne_f32_e32 v22, v22
	v_med3_f32 v22, v22, s33, v13
	v_cvt_i32_f32_e32 v21, v21
	v_cvt_i32_f32_e32 v22, v22
	v_and_b32_e32 v21, 15, v21
	v_and_b32_e32 v22, 15, v22
	v_lshl_or_b32 v210, v21, 8, v210
	v_lshl_or_b32 v214, v22, 8, v214
	v_mul_f32_e32 v23, v147, v11
	v_rndne_f32_e32 v23, v23
	v_med3_f32 v23, v23, s33, v13
	v_fma_f32 v30, -v7, v23, v147
	v_mul_f32_e32 v30, v30, v12
	v_rndne_f32_e32 v30, v30
	v_med3_f32 v30, v30, s33, v13
	v_cvt_i32_f32_e32 v23, v23
	v_cvt_i32_f32_e32 v30, v30
	v_and_b32_e32 v23, 15, v23
	v_and_b32_e32 v30, 15, v30
	v_lshl_or_b32 v210, v23, 12, v210
	v_lshl_or_b32 v214, v30, 12, v214
	v_mul_f32_e32 v21, v148, v11
	v_rndne_f32_e32 v21, v21
	v_med3_f32 v21, v21, s33, v13
	v_fma_f32 v22, -v7, v21, v148
	v_mul_f32_e32 v22, v22, v12
	v_rndne_f32_e32 v22, v22
	v_med3_f32 v22, v22, s33, v13
	v_cvt_i32_f32_e32 v21, v21
	v_cvt_i32_f32_e32 v22, v22
	v_and_b32_e32 v21, 15, v21
	v_and_b32_e32 v22, 15, v22
	v_lshl_or_b32 v210, v21, 16, v210
	v_lshl_or_b32 v214, v22, 16, v214
	v_mul_f32_e32 v23, v149, v11
	v_rndne_f32_e32 v23, v23
	v_med3_f32 v23, v23, s33, v13
	v_fma_f32 v30, -v7, v23, v149
	v_mul_f32_e32 v30, v30, v12
	v_rndne_f32_e32 v30, v30
	v_med3_f32 v30, v30, s33, v13
	v_cvt_i32_f32_e32 v23, v23
	v_cvt_i32_f32_e32 v30, v30
	v_and_b32_e32 v23, 15, v23
	v_and_b32_e32 v30, 15, v30
	v_lshl_or_b32 v210, v23, 20, v210
	v_lshl_or_b32 v214, v30, 20, v214
	v_mul_f32_e32 v21, v150, v11
	v_rndne_f32_e32 v21, v21
	v_med3_f32 v21, v21, s33, v13
	v_fma_f32 v22, -v7, v21, v150
	v_mul_f32_e32 v22, v22, v12
	v_rndne_f32_e32 v22, v22
	v_med3_f32 v22, v22, s33, v13
	v_cvt_i32_f32_e32 v21, v21
	v_cvt_i32_f32_e32 v22, v22
	v_and_b32_e32 v21, 15, v21
	v_and_b32_e32 v22, 15, v22
	v_lshl_or_b32 v210, v21, 24, v210
	v_lshl_or_b32 v214, v22, 24, v214
	v_mul_f32_e32 v23, v151, v11
	v_rndne_f32_e32 v23, v23
	v_med3_f32 v23, v23, s33, v13
	v_fma_f32 v30, -v7, v23, v151
	v_mul_f32_e32 v30, v30, v12
	v_rndne_f32_e32 v30, v30
	v_med3_f32 v30, v30, s33, v13
	v_cvt_i32_f32_e32 v23, v23
	v_cvt_i32_f32_e32 v30, v30
	v_lshl_or_b32 v210, v23, 28, v210
	v_lshl_or_b32 v214, v30, 28, v214
	v_mul_f32_e32 v21, v152, v11
	v_rndne_f32_e32 v21, v21
	v_med3_f32 v21, v21, s33, v13
	v_fma_f32 v22, -v7, v21, v152
	v_mul_f32_e32 v22, v22, v12
	v_rndne_f32_e32 v22, v22
	v_med3_f32 v22, v22, s33, v13
	v_cvt_i32_f32_e32 v21, v21
	v_cvt_i32_f32_e32 v22, v22
	v_and_b32_e32 v211, 15, v21
	v_and_b32_e32 v215, 15, v22
	v_mul_f32_e32 v23, v153, v11
	v_rndne_f32_e32 v23, v23
	v_med3_f32 v23, v23, s33, v13
	v_fma_f32 v30, -v7, v23, v153
	v_mul_f32_e32 v30, v30, v12
	v_rndne_f32_e32 v30, v30
	v_med3_f32 v30, v30, s33, v13
	v_cvt_i32_f32_e32 v23, v23
	v_cvt_i32_f32_e32 v30, v30
	v_and_b32_e32 v23, 15, v23
	v_and_b32_e32 v30, 15, v30
	v_lshl_or_b32 v211, v23, 4, v211
	v_lshl_or_b32 v215, v30, 4, v215
	v_mul_f32_e32 v21, v154, v11
	v_rndne_f32_e32 v21, v21
	v_med3_f32 v21, v21, s33, v13
	v_fma_f32 v22, -v7, v21, v154
	v_mul_f32_e32 v22, v22, v12
	v_rndne_f32_e32 v22, v22
	v_med3_f32 v22, v22, s33, v13
	v_cvt_i32_f32_e32 v21, v21
	v_cvt_i32_f32_e32 v22, v22
	v_and_b32_e32 v21, 15, v21
	v_and_b32_e32 v22, 15, v22
	v_lshl_or_b32 v211, v21, 8, v211
	v_lshl_or_b32 v215, v22, 8, v215
	v_mul_f32_e32 v23, v155, v11
	v_rndne_f32_e32 v23, v23
	v_med3_f32 v23, v23, s33, v13
	v_fma_f32 v30, -v7, v23, v155
	v_mul_f32_e32 v30, v30, v12
	v_rndne_f32_e32 v30, v30
	v_med3_f32 v30, v30, s33, v13
	v_cvt_i32_f32_e32 v23, v23
	v_cvt_i32_f32_e32 v30, v30
	v_and_b32_e32 v23, 15, v23
	v_and_b32_e32 v30, 15, v30
	v_lshl_or_b32 v211, v23, 12, v211
	v_lshl_or_b32 v215, v30, 12, v215
	v_mul_f32_e32 v21, v156, v11
	v_rndne_f32_e32 v21, v21
	v_med3_f32 v21, v21, s33, v13
	v_fma_f32 v22, -v7, v21, v156
	v_mul_f32_e32 v22, v22, v12
	v_rndne_f32_e32 v22, v22
	v_med3_f32 v22, v22, s33, v13
	v_cvt_i32_f32_e32 v21, v21
	v_cvt_i32_f32_e32 v22, v22
	v_and_b32_e32 v21, 15, v21
	v_and_b32_e32 v22, 15, v22
	v_lshl_or_b32 v211, v21, 16, v211
	v_lshl_or_b32 v215, v22, 16, v215
	v_mul_f32_e32 v23, v157, v11
	v_rndne_f32_e32 v23, v23
	v_med3_f32 v23, v23, s33, v13
	v_fma_f32 v30, -v7, v23, v157
	v_mul_f32_e32 v30, v30, v12
	v_rndne_f32_e32 v30, v30
	v_med3_f32 v30, v30, s33, v13
	v_cvt_i32_f32_e32 v23, v23
	v_cvt_i32_f32_e32 v30, v30
	v_and_b32_e32 v23, 15, v23
	v_and_b32_e32 v30, 15, v30
	v_lshl_or_b32 v211, v23, 20, v211
	v_lshl_or_b32 v215, v30, 20, v215
	v_mul_f32_e32 v21, v158, v11
	v_rndne_f32_e32 v21, v21
	v_med3_f32 v21, v21, s33, v13
	v_fma_f32 v22, -v7, v21, v158
	v_mul_f32_e32 v22, v22, v12
	v_rndne_f32_e32 v22, v22
	v_med3_f32 v22, v22, s33, v13
	v_cvt_i32_f32_e32 v21, v21
	v_cvt_i32_f32_e32 v22, v22
	v_and_b32_e32 v21, 15, v21
	v_and_b32_e32 v22, 15, v22
	v_lshl_or_b32 v211, v21, 24, v211
	v_lshl_or_b32 v215, v22, 24, v215
	v_mul_f32_e32 v23, v159, v11
	v_rndne_f32_e32 v23, v23
	v_med3_f32 v23, v23, s33, v13
	v_fma_f32 v30, -v7, v23, v159
	v_mul_f32_e32 v30, v30, v12
	v_rndne_f32_e32 v30, v30
	v_med3_f32 v30, v30, s33, v13
	v_cvt_i32_f32_e32 v23, v23
	v_cvt_i32_f32_e32 v30, v30
	v_lshl_or_b32 v211, v23, 28, v211
	v_lshl_or_b32 v215, v30, 28, v215
	s_waitcnt vmcnt(32)
	v_mul_f32_e32 v2, v24, v10
	v_mul_f32_e32 v236, v236, v2
	v_mul_f32_e32 v237, v237, v2
	v_mul_f32_e32 v238, v238, v234
	v_mul_f32_e32 v239, v239, v235
	ds_write_b32 v5, v236
	ds_write_b32 v5, v237 offset:256
	ds_write_b32 v5, v238 offset:512
	ds_write_b32 v5, v239 offset:768
	s_mov_b32 s86, 7

.Lpb_926:
	s_waitcnt lgkmcnt(0)
	v_and_b32_e32 v0, 63, v204
	v_lshlrev_b32_e32 v1, 12, v4
	v_lshl_add_u32 v1, v0, 5, v1
	v_add_u32_e32 v1, 0x13288000, v1
	global_load_dwordx4 v[216:219], v1, s[94:95]
	global_load_dwordx4 v[220:223], v1, s[94:95] offset:16
	global_load_dwordx4 v[224:227], v1, s[94:95] offset:2048
	global_load_dwordx4 v[228:231], v1, s[94:95] offset:2064
	ds_read_b32 v232, v170
	ds_read_b32 v233, v170 offset:256
	ds_read_b32 v234, v170 offset:512
	ds_read_b32 v235, v170 offset:768
	v_lshlrev_b32_e32 v28, 3, v0
	v_add_u32_e32 v29, 0x4008000, v28
	v_add_u32_e32 v28, 0x8000, v28
	s_waitcnt lgkmcnt(0)
	v_lshlrev_b32_e32 v2, 2, v232
	v_lshlrev_b32_e32 v3, 2, v233
	global_load_dword v236, v2, s[74:75]
	global_load_dword v237, v3, s[74:75]
	global_load_dword v238, v2, s[76:77]
	global_load_dword v239, v3, s[76:77]
	v_mov_b32_e32 v32, 0
	v_mov_b32_e32 v33, 0
	v_mov_b32_e32 v34, 0
	v_mov_b32_e32 v35, 0
	v_mov_b32_e32 v36, 0
	v_mov_b32_e32 v37, 0
	v_mov_b32_e32 v38, 0
	v_mov_b32_e32 v39, 0
	v_mov_b32_e32 v40, 0
	v_mov_b32_e32 v41, 0
	v_mov_b32_e32 v42, 0
	v_mov_b32_e32 v43, 0
	v_mov_b32_e32 v44, 0
	v_mov_b32_e32 v45, 0
	v_mov_b32_e32 v46, 0
	v_mov_b32_e32 v47, 0
	v_mov_b32_e32 v48, 0
	v_mov_b32_e32 v49, 0
	v_mov_b32_e32 v50, 0
	v_mov_b32_e32 v51, 0
	v_mov_b32_e32 v52, 0
	v_mov_b32_e32 v53, 0
	v_mov_b32_e32 v54, 0
	v_mov_b32_e32 v55, 0
	v_mov_b32_e32 v56, 0
	v_mov_b32_e32 v57, 0
	v_mov_b32_e32 v58, 0
	v_mov_b32_e32 v59, 0
	v_mov_b32_e32 v60, 0
	v_mov_b32_e32 v61, 0
	v_mov_b32_e32 v62, 0
	v_mov_b32_e32 v63, 0
	v_lshlrev_b32_e32 v2, 2, v0
	v_sub_u32_e32 v25, v170, v2
	v_add_u32_e32 v5, 0x1000, v170
	v_lshrrev_b32_e32 v2, 4, v0
	v_lshrrev_b32_e32 v3, 5, v0
	v_and_b32_e32 v2, 1, v2
	v_lshl_or_b32 v2, v2, 1, v3
	v_add_u32_e32 v3, 0x1000, v25
	v_lshl_add_u32 v26, v2, 2, v3
	v_add_u32_e32 v27, 16, v26
	s_lshr_b32 s96, s88, 4
	v_add_u32_e32 v25, s96, v25
	v_add_u32_e32 v26, s96, v26
	v_add_u32_e32 v27, s96, v27
	ds_read_b128 v[10:13], v25
	ds_read_b128 v[18:21], v25 offset:16
	v_add_u32_e32 v25, 32, v25
	s_waitcnt lgkmcnt(0)
	v_readfirstlane_b32 s33, v10
	s_lshl_b32 s33, s33, 10
	s_add_u32 s72, s94, s33
	s_addc_u32 s73, s95, 0
	global_load_dwordx2 v[64:65], v28, s[72:73]
	global_load_dwordx2 v[66:67], v28, s[72:73] offset:512
	global_load_dwordx2 v[96:97], v29, s[72:73]
	global_load_dwordx2 v[98:99], v29, s[72:73] offset:512
	v_readfirstlane_b32 s33, v11
	s_lshl_b32 s33, s33, 10
	s_add_u32 s72, s94, s33
	s_addc_u32 s73, s95, 0
	global_load_dwordx2 v[68:69], v28, s[72:73]
	global_load_dwordx2 v[70:71], v28, s[72:73] offset:512
	global_load_dwordx2 v[100:101], v29, s[72:73]
	global_load_dwordx2 v[102:103], v29, s[72:73] offset:512
	v_readfirstlane_b32 s33, v12
	s_lshl_b32 s33, s33, 10
	s_add_u32 s72, s94, s33
	s_addc_u32 s73, s95, 0
	global_load_dwordx2 v[72:73], v28, s[72:73]
	global_load_dwordx2 v[74:75], v28, s[72:73] offset:512
	global_load_dwordx2 v[104:105], v29, s[72:73]
	global_load_dwordx2 v[106:107], v29, s[72:73] offset:512
	v_readfirstlane_b32 s33, v13
	s_lshl_b32 s33, s33, 10
	s_add_u32 s72, s94, s33
	s_addc_u32 s73, s95, 0
	global_load_dwordx2 v[76:77], v28, s[72:73]
	global_load_dwordx2 v[78:79], v28, s[72:73] offset:512
	global_load_dwordx2 v[108:109], v29, s[72:73]
	global_load_dwordx2 v[110:111], v29, s[72:73] offset:512
	v_readfirstlane_b32 s33, v18
	s_lshl_b32 s33, s33, 10
	s_add_u32 s72, s94, s33
	s_addc_u32 s73, s95, 0
	global_load_dwordx2 v[80:81], v28, s[72:73]
	global_load_dwordx2 v[82:83], v28, s[72:73] offset:512
	global_load_dwordx2 v[112:113], v29, s[72:73]
	global_load_dwordx2 v[114:115], v29, s[72:73] offset:512
	v_readfirstlane_b32 s33, v19
	s_lshl_b32 s33, s33, 10
	s_add_u32 s72, s94, s33
	s_addc_u32 s73, s95, 0
	global_load_dwordx2 v[84:85], v28, s[72:73]
	global_load_dwordx2 v[86:87], v28, s[72:73] offset:512
	global_load_dwordx2 v[116:117], v29, s[72:73]
	global_load_dwordx2 v[118:119], v29, s[72:73] offset:512
	v_readfirstlane_b32 s33, v20
	s_lshl_b32 s33, s33, 10
	s_add_u32 s72, s94, s33
	s_addc_u32 s73, s95, 0
	global_load_dwordx2 v[88:89], v28, s[72:73]
	global_load_dwordx2 v[90:91], v28, s[72:73] offset:512
	global_load_dwordx2 v[120:121], v29, s[72:73]
	global_load_dwordx2 v[122:123], v29, s[72:73] offset:512
	v_readfirstlane_b32 s33, v21
	s_lshl_b32 s33, s33, 10
	s_add_u32 s72, s94, s33
	s_addc_u32 s73, s95, 0
	global_load_dwordx2 v[92:93], v28, s[72:73]
	global_load_dwordx2 v[94:95], v28, s[72:73] offset:512
	global_load_dwordx2 v[124:125], v29, s[72:73]
	global_load_dwordx2 v[126:127], v29, s[72:73] offset:512
	s_waitcnt vmcnt(36)
	v_lshlrev_b32_e32 v128, 16, v216
	v_and_b32_e32 v129, 0xffff0000, v216
	v_lshlrev_b32_e32 v130, 16, v217
	v_and_b32_e32 v131, 0xffff0000, v217
	v_lshlrev_b32_e32 v132, 16, v218
	v_and_b32_e32 v133, 0xffff0000, v218
	v_lshlrev_b32_e32 v134, 16, v219
	v_and_b32_e32 v135, 0xffff0000, v219
	v_lshlrev_b32_e32 v136, 16, v220
	v_and_b32_e32 v137, 0xffff0000, v220
	v_lshlrev_b32_e32 v138, 16, v221
	v_and_b32_e32 v139, 0xffff0000, v221
	v_lshlrev_b32_e32 v140, 16, v222
	v_and_b32_e32 v141, 0xffff0000, v222
	v_lshlrev_b32_e32 v142, 16, v223
	v_and_b32_e32 v143, 0xffff0000, v223
	v_lshlrev_b32_e32 v144, 16, v224
	v_and_b32_e32 v145, 0xffff0000, v224
	v_lshlrev_b32_e32 v146, 16, v225
	v_and_b32_e32 v147, 0xffff0000, v225
	v_lshlrev_b32_e32 v148, 16, v226
	v_and_b32_e32 v149, 0xffff0000, v226
	v_lshlrev_b32_e32 v150, 16, v227
	v_and_b32_e32 v151, 0xffff0000, v227
	v_lshlrev_b32_e32 v152, 16, v228
	v_and_b32_e32 v153, 0xffff0000, v228
	v_lshlrev_b32_e32 v154, 16, v229
	v_and_b32_e32 v155, 0xffff0000, v229
	v_lshlrev_b32_e32 v156, 16, v230
	v_and_b32_e32 v157, 0xffff0000, v230
	v_lshlrev_b32_e32 v158, 16, v231
	v_and_b32_e32 v159, 0xffff0000, v231
	v_max3_f32 v6, |v128|, |v129|, |v130|
	v_max3_f32 v6, v6, |v131|, |v132|
	v_max3_f32 v6, v6, |v133|, |v134|
	v_max3_f32 v6, v6, |v135|, |v136|
	v_max3_f32 v6, v6, |v137|, |v138|
	v_max3_f32 v6, v6, |v139|, |v140|
	v_max3_f32 v6, v6, |v141|, |v142|
	v_max3_f32 v6, v6, |v143|, |v144|
	v_max3_f32 v6, v6, |v145|, |v146|
	v_max3_f32 v6, v6, |v147|, |v148|
	v_max3_f32 v6, v6, |v149|, |v150|
	v_max3_f32 v6, v6, |v151|, |v152|
	v_max3_f32 v6, v6, |v153|, |v154|
	v_max3_f32 v6, v6, |v155|, |v156|
	v_max3_f32 v6, v6, |v157|, |v158|
	v_max_f32_e64 v6, v6, |v159|
	v_mov_b32_e32 v2, v6
	v_mov_b32_e32 v3, v6
	s_nop 1
	v_permlane32_swap_b32_e32 v2, v3
	v_max_f32_e32 v6, v2, v3
	v_mov_b32_e32 v2, v6
	v_mov_b32_e32 v3, v6
	s_nop 1
	v_permlane16_swap_b32_e32 v2, v3
	v_max_f32_e32 v6, v2, v3
	s_nop 1
	v_max_f32_dpp v6, v6, v6 row_ror:8 row_mask:0xf bank_mask:0xf
	s_nop 1
	v_max_f32_dpp v6, v6, v6 row_ror:4 row_mask:0xf bank_mask:0xf
	s_nop 1
	v_max_f32_dpp v6, v6, v6 row_ror:2 row_mask:0xf bank_mask:0xf
	s_nop 1
	v_max_f32_dpp v6, v6, v6 row_ror:1 row_mask:0xf bank_mask:0xf
	v_mul_f32_e32 v7, 0x3e124925, v6
	v_cmp_lt_f32_e32 vcc, 0, v6
	s_nop 1
	v_cndmask_b32_e32 v7, 1.0, v7, vcc
	v_mul_f32_e32 v10, 0x3d924925, v7
	v_rcp_f32_e32 v11, v7
	v_rcp_f32_e32 v12, v10
	s_mov_b32 s33, 0xc0e00000
	v_mov_b32_e32 v13, 0x40e00000
	v_mul_f32_e32 v21, v128, v11
	v_rndne_f32_e32 v21, v21
	v_med3_f32 v21, v21, s33, v13
	v_fma_f32 v22, -v7, v21, v128
	v_mul_f32_e32 v22, v22, v12
	v_rndne_f32_e32 v22, v22
	v_med3_f32 v22, v22, s33, v13
	v_cvt_i32_f32_e32 v21, v21
	v_cvt_i32_f32_e32 v22, v22
	v_and_b32_e32 v208, 15, v21
	v_and_b32_e32 v212, 15, v22
	v_mul_f32_e32 v23, v129, v11
	v_rndne_f32_e32 v23, v23
	v_med3_f32 v23, v23, s33, v13
	v_fma_f32 v30, -v7, v23, v129
	v_mul_f32_e32 v30, v30, v12
	v_rndne_f32_e32 v30, v30
	v_med3_f32 v30, v30, s33, v13
	v_cvt_i32_f32_e32 v23, v23
	v_cvt_i32_f32_e32 v30, v30
	v_and_b32_e32 v23, 15, v23
	v_and_b32_e32 v30, 15, v30
	v_lshl_or_b32 v208, v23, 4, v208
	v_lshl_or_b32 v212, v30, 4, v212
	v_mul_f32_e32 v21, v130, v11
	v_rndne_f32_e32 v21, v21
	v_med3_f32 v21, v21, s33, v13
	v_fma_f32 v22, -v7, v21, v130
	v_mul_f32_e32 v22, v22, v12
	v_rndne_f32_e32 v22, v22
	v_med3_f32 v22, v22, s33, v13
	v_cvt_i32_f32_e32 v21, v21
	v_cvt_i32_f32_e32 v22, v22
	v_and_b32_e32 v21, 15, v21
	v_and_b32_e32 v22, 15, v22
	v_lshl_or_b32 v208, v21, 8, v208
	v_lshl_or_b32 v212, v22, 8, v212
	v_mul_f32_e32 v23, v131, v11
	v_rndne_f32_e32 v23, v23
	v_med3_f32 v23, v23, s33, v13
	v_fma_f32 v30, -v7, v23, v131
	v_mul_f32_e32 v30, v30, v12
	v_rndne_f32_e32 v30, v30
	v_med3_f32 v30, v30, s33, v13
	v_cvt_i32_f32_e32 v23, v23
	v_cvt_i32_f32_e32 v30, v30
	v_and_b32_e32 v23, 15, v23
	v_and_b32_e32 v30, 15, v30
	v_lshl_or_b32 v208, v23, 12, v208
	v_lshl_or_b32 v212, v30, 12, v212
	v_mul_f32_e32 v21, v132, v11
	v_rndne_f32_e32 v21, v21
	v_med3_f32 v21, v21, s33, v13
	v_fma_f32 v22, -v7, v21, v132
	v_mul_f32_e32 v22, v22, v12
	v_rndne_f32_e32 v22, v22
	v_med3_f32 v22, v22, s33, v13
	v_cvt_i32_f32_e32 v21, v21
	v_cvt_i32_f32_e32 v22, v22
	v_and_b32_e32 v21, 15, v21
	v_and_b32_e32 v22, 15, v22
	v_lshl_or_b32 v208, v21, 16, v208
	v_lshl_or_b32 v212, v22, 16, v212
	v_mul_f32_e32 v23, v133, v11
	v_rndne_f32_e32 v23, v23
	v_med3_f32 v23, v23, s33, v13
	v_fma_f32 v30, -v7, v23, v133
	v_mul_f32_e32 v30, v30, v12
	v_rndne_f32_e32 v30, v30
	v_med3_f32 v30, v30, s33, v13
	v_cvt_i32_f32_e32 v23, v23
	v_cvt_i32_f32_e32 v30, v30
	v_and_b32_e32 v23, 15, v23
	v_and_b32_e32 v30, 15, v30
	v_lshl_or_b32 v208, v23, 20, v208
	v_lshl_or_b32 v212, v30, 20, v212
	v_mul_f32_e32 v21, v134, v11
	v_rndne_f32_e32 v21, v21
	v_med3_f32 v21, v21, s33, v13
	v_fma_f32 v22, -v7, v21, v134
	v_mul_f32_e32 v22, v22, v12
	v_rndne_f32_e32 v22, v22
	v_med3_f32 v22, v22, s33, v13
	v_cvt_i32_f32_e32 v21, v21
	v_cvt_i32_f32_e32 v22, v22
	v_and_b32_e32 v21, 15, v21
	v_and_b32_e32 v22, 15, v22
	v_lshl_or_b32 v208, v21, 24, v208
	v_lshl_or_b32 v212, v22, 24, v212
	v_mul_f32_e32 v23, v135, v11
	v_rndne_f32_e32 v23, v23
	v_med3_f32 v23, v23, s33, v13
	v_fma_f32 v30, -v7, v23, v135
	v_mul_f32_e32 v30, v30, v12
	v_rndne_f32_e32 v30, v30
	v_med3_f32 v30, v30, s33, v13
	v_cvt_i32_f32_e32 v23, v23
	v_cvt_i32_f32_e32 v30, v30
	v_lshl_or_b32 v208, v23, 28, v208
	v_lshl_or_b32 v212, v30, 28, v212
	v_mul_f32_e32 v21, v136, v11
	v_rndne_f32_e32 v21, v21
	v_med3_f32 v21, v21, s33, v13
	v_fma_f32 v22, -v7, v21, v136
	v_mul_f32_e32 v22, v22, v12
	v_rndne_f32_e32 v22, v22
	v_med3_f32 v22, v22, s33, v13
	v_cvt_i32_f32_e32 v21, v21
	v_cvt_i32_f32_e32 v22, v22
	v_and_b32_e32 v209, 15, v21
	v_and_b32_e32 v213, 15, v22
	v_mul_f32_e32 v23, v137, v11
	v_rndne_f32_e32 v23, v23
	v_med3_f32 v23, v23, s33, v13
	v_fma_f32 v30, -v7, v23, v137
	v_mul_f32_e32 v30, v30, v12
	v_rndne_f32_e32 v30, v30
	v_med3_f32 v30, v30, s33, v13
	v_cvt_i32_f32_e32 v23, v23
	v_cvt_i32_f32_e32 v30, v30
	v_and_b32_e32 v23, 15, v23
	v_and_b32_e32 v30, 15, v30
	v_lshl_or_b32 v209, v23, 4, v209
	v_lshl_or_b32 v213, v30, 4, v213
	v_mul_f32_e32 v21, v138, v11
	v_rndne_f32_e32 v21, v21
	v_med3_f32 v21, v21, s33, v13
	v_fma_f32 v22, -v7, v21, v138
	v_mul_f32_e32 v22, v22, v12
	v_rndne_f32_e32 v22, v22
	v_med3_f32 v22, v22, s33, v13
	v_cvt_i32_f32_e32 v21, v21
	v_cvt_i32_f32_e32 v22, v22
	v_and_b32_e32 v21, 15, v21
	v_and_b32_e32 v22, 15, v22
	v_lshl_or_b32 v209, v21, 8, v209
	v_lshl_or_b32 v213, v22, 8, v213
	v_mul_f32_e32 v23, v139, v11
	v_rndne_f32_e32 v23, v23
	v_med3_f32 v23, v23, s33, v13
	v_fma_f32 v30, -v7, v23, v139
	v_mul_f32_e32 v30, v30, v12
	v_rndne_f32_e32 v30, v30
	v_med3_f32 v30, v30, s33, v13
	v_cvt_i32_f32_e32 v23, v23
	v_cvt_i32_f32_e32 v30, v30
	v_and_b32_e32 v23, 15, v23
	v_and_b32_e32 v30, 15, v30
	v_lshl_or_b32 v209, v23, 12, v209
	v_lshl_or_b32 v213, v30, 12, v213
	v_mul_f32_e32 v21, v140, v11
	v_rndne_f32_e32 v21, v21
	v_med3_f32 v21, v21, s33, v13
	v_fma_f32 v22, -v7, v21, v140
	v_mul_f32_e32 v22, v22, v12
	v_rndne_f32_e32 v22, v22
	v_med3_f32 v22, v22, s33, v13
	v_cvt_i32_f32_e32 v21, v21
	v_cvt_i32_f32_e32 v22, v22
	v_and_b32_e32 v21, 15, v21
	v_and_b32_e32 v22, 15, v22
	v_lshl_or_b32 v209, v21, 16, v209
	v_lshl_or_b32 v213, v22, 16, v213
	v_mul_f32_e32 v23, v141, v11
	v_rndne_f32_e32 v23, v23
	v_med3_f32 v23, v23, s33, v13
	v_fma_f32 v30, -v7, v23, v141
	v_mul_f32_e32 v30, v30, v12
	v_rndne_f32_e32 v30, v30
	v_med3_f32 v30, v30, s33, v13
	v_cvt_i32_f32_e32 v23, v23
	v_cvt_i32_f32_e32 v30, v30
	v_and_b32_e32 v23, 15, v23
	v_and_b32_e32 v30, 15, v30
	v_lshl_or_b32 v209, v23, 20, v209
	v_lshl_or_b32 v213, v30, 20, v213
	v_mul_f32_e32 v21, v142, v11
	v_rndne_f32_e32 v21, v21
	v_med3_f32 v21, v21, s33, v13
	v_fma_f32 v22, -v7, v21, v142
	v_mul_f32_e32 v22, v22, v12
	v_rndne_f32_e32 v22, v22
	v_med3_f32 v22, v22, s33, v13
	v_cvt_i32_f32_e32 v21, v21
	v_cvt_i32_f32_e32 v22, v22
	v_and_b32_e32 v21, 15, v21
	v_and_b32_e32 v22, 15, v22
	v_lshl_or_b32 v209, v21, 24, v209
	v_lshl_or_b32 v213, v22, 24, v213
	v_mul_f32_e32 v23, v143, v11
	v_rndne_f32_e32 v23, v23
	v_med3_f32 v23, v23, s33, v13
	v_fma_f32 v30, -v7, v23, v143
	v_mul_f32_e32 v30, v30, v12
	v_rndne_f32_e32 v30, v30
	v_med3_f32 v30, v30, s33, v13
	v_cvt_i32_f32_e32 v23, v23
	v_cvt_i32_f32_e32 v30, v30
	v_lshl_or_b32 v209, v23, 28, v209
	v_lshl_or_b32 v213, v30, 28, v213
	v_mul_f32_e32 v21, v144, v11
	v_rndne_f32_e32 v21, v21
	v_med3_f32 v21, v21, s33, v13
	v_fma_f32 v22, -v7, v21, v144
	v_mul_f32_e32 v22, v22, v12
	v_rndne_f32_e32 v22, v22
	v_med3_f32 v22, v22, s33, v13
	v_cvt_i32_f32_e32 v21, v21
	v_cvt_i32_f32_e32 v22, v22
	v_and_b32_e32 v210, 15, v21
	v_and_b32_e32 v214, 15, v22
	v_mul_f32_e32 v23, v145, v11
	v_rndne_f32_e32 v23, v23
	v_med3_f32 v23, v23, s33, v13
	v_fma_f32 v30, -v7, v23, v145
	v_mul_f32_e32 v30, v30, v12
	v_rndne_f32_e32 v30, v30
	v_med3_f32 v30, v30, s33, v13
	v_cvt_i32_f32_e32 v23, v23
	v_cvt_i32_f32_e32 v30, v30
	v_and_b32_e32 v23, 15, v23
	v_and_b32_e32 v30, 15, v30
	v_lshl_or_b32 v210, v23, 4, v210
	v_lshl_or_b32 v214, v30, 4, v214
	v_mul_f32_e32 v21, v146, v11
	v_rndne_f32_e32 v21, v21
	v_med3_f32 v21, v21, s33, v13
	v_fma_f32 v22, -v7, v21, v146
	v_mul_f32_e32 v22, v22, v12
	v_rndne_f32_e32 v22, v22
	v_med3_f32 v22, v22, s33, v13
	v_cvt_i32_f32_e32 v21, v21
	v_cvt_i32_f32_e32 v22, v22
	v_and_b32_e32 v21, 15, v21
	v_and_b32_e32 v22, 15, v22
	v_lshl_or_b32 v210, v21, 8, v210
	v_lshl_or_b32 v214, v22, 8, v214
	v_mul_f32_e32 v23, v147, v11
	v_rndne_f32_e32 v23, v23
	v_med3_f32 v23, v23, s33, v13
	v_fma_f32 v30, -v7, v23, v147
	v_mul_f32_e32 v30, v30, v12
	v_rndne_f32_e32 v30, v30
	v_med3_f32 v30, v30, s33, v13
	v_cvt_i32_f32_e32 v23, v23
	v_cvt_i32_f32_e32 v30, v30
	v_and_b32_e32 v23, 15, v23
	v_and_b32_e32 v30, 15, v30
	v_lshl_or_b32 v210, v23, 12, v210
	v_lshl_or_b32 v214, v30, 12, v214
	v_mul_f32_e32 v21, v148, v11
	v_rndne_f32_e32 v21, v21
	v_med3_f32 v21, v21, s33, v13
	v_fma_f32 v22, -v7, v21, v148
	v_mul_f32_e32 v22, v22, v12
	v_rndne_f32_e32 v22, v22
	v_med3_f32 v22, v22, s33, v13
	v_cvt_i32_f32_e32 v21, v21
	v_cvt_i32_f32_e32 v22, v22
	v_and_b32_e32 v21, 15, v21
	v_and_b32_e32 v22, 15, v22
	v_lshl_or_b32 v210, v21, 16, v210
	v_lshl_or_b32 v214, v22, 16, v214
	v_mul_f32_e32 v23, v149, v11
	v_rndne_f32_e32 v23, v23
	v_med3_f32 v23, v23, s33, v13
	v_fma_f32 v30, -v7, v23, v149
	v_mul_f32_e32 v30, v30, v12
	v_rndne_f32_e32 v30, v30
	v_med3_f32 v30, v30, s33, v13
	v_cvt_i32_f32_e32 v23, v23
	v_cvt_i32_f32_e32 v30, v30
	v_and_b32_e32 v23, 15, v23
	v_and_b32_e32 v30, 15, v30
	v_lshl_or_b32 v210, v23, 20, v210
	v_lshl_or_b32 v214, v30, 20, v214
	v_mul_f32_e32 v21, v150, v11
	v_rndne_f32_e32 v21, v21
	v_med3_f32 v21, v21, s33, v13
	v_fma_f32 v22, -v7, v21, v150
	v_mul_f32_e32 v22, v22, v12
	v_rndne_f32_e32 v22, v22
	v_med3_f32 v22, v22, s33, v13
	v_cvt_i32_f32_e32 v21, v21
	v_cvt_i32_f32_e32 v22, v22
	v_and_b32_e32 v21, 15, v21
	v_and_b32_e32 v22, 15, v22
	v_lshl_or_b32 v210, v21, 24, v210
	v_lshl_or_b32 v214, v22, 24, v214
	v_mul_f32_e32 v23, v151, v11
	v_rndne_f32_e32 v23, v23
	v_med3_f32 v23, v23, s33, v13
	v_fma_f32 v30, -v7, v23, v151
	v_mul_f32_e32 v30, v30, v12
	v_rndne_f32_e32 v30, v30
	v_med3_f32 v30, v30, s33, v13
	v_cvt_i32_f32_e32 v23, v23
	v_cvt_i32_f32_e32 v30, v30
	v_lshl_or_b32 v210, v23, 28, v210
	v_lshl_or_b32 v214, v30, 28, v214
	v_mul_f32_e32 v21, v152, v11
	v_rndne_f32_e32 v21, v21
	v_med3_f32 v21, v21, s33, v13
	v_fma_f32 v22, -v7, v21, v152
	v_mul_f32_e32 v22, v22, v12
	v_rndne_f32_e32 v22, v22
	v_med3_f32 v22, v22, s33, v13
	v_cvt_i32_f32_e32 v21, v21
	v_cvt_i32_f32_e32 v22, v22
	v_and_b32_e32 v211, 15, v21
	v_and_b32_e32 v215, 15, v22
	v_mul_f32_e32 v23, v153, v11
	v_rndne_f32_e32 v23, v23
	v_med3_f32 v23, v23, s33, v13
	v_fma_f32 v30, -v7, v23, v153
	v_mul_f32_e32 v30, v30, v12
	v_rndne_f32_e32 v30, v30
	v_med3_f32 v30, v30, s33, v13
	v_cvt_i32_f32_e32 v23, v23
	v_cvt_i32_f32_e32 v30, v30
	v_and_b32_e32 v23, 15, v23
	v_and_b32_e32 v30, 15, v30
	v_lshl_or_b32 v211, v23, 4, v211
	v_lshl_or_b32 v215, v30, 4, v215
	v_mul_f32_e32 v21, v154, v11
	v_rndne_f32_e32 v21, v21
	v_med3_f32 v21, v21, s33, v13
	v_fma_f32 v22, -v7, v21, v154
	v_mul_f32_e32 v22, v22, v12
	v_rndne_f32_e32 v22, v22
	v_med3_f32 v22, v22, s33, v13
	v_cvt_i32_f32_e32 v21, v21
	v_cvt_i32_f32_e32 v22, v22
	v_and_b32_e32 v21, 15, v21
	v_and_b32_e32 v22, 15, v22
	v_lshl_or_b32 v211, v21, 8, v211
	v_lshl_or_b32 v215, v22, 8, v215
	v_mul_f32_e32 v23, v155, v11
	v_rndne_f32_e32 v23, v23
	v_med3_f32 v23, v23, s33, v13
	v_fma_f32 v30, -v7, v23, v155
	v_mul_f32_e32 v30, v30, v12
	v_rndne_f32_e32 v30, v30
	v_med3_f32 v30, v30, s33, v13
	v_cvt_i32_f32_e32 v23, v23
	v_cvt_i32_f32_e32 v30, v30
	v_and_b32_e32 v23, 15, v23
	v_and_b32_e32 v30, 15, v30
	v_lshl_or_b32 v211, v23, 12, v211
	v_lshl_or_b32 v215, v30, 12, v215
	v_mul_f32_e32 v21, v156, v11
	v_rndne_f32_e32 v21, v21
	v_med3_f32 v21, v21, s33, v13
	v_fma_f32 v22, -v7, v21, v156
	v_mul_f32_e32 v22, v22, v12
	v_rndne_f32_e32 v22, v22
	v_med3_f32 v22, v22, s33, v13
	v_cvt_i32_f32_e32 v21, v21
	v_cvt_i32_f32_e32 v22, v22
	v_and_b32_e32 v21, 15, v21
	v_and_b32_e32 v22, 15, v22
	v_lshl_or_b32 v211, v21, 16, v211
	v_lshl_or_b32 v215, v22, 16, v215
	v_mul_f32_e32 v23, v157, v11
	v_rndne_f32_e32 v23, v23
	v_med3_f32 v23, v23, s33, v13
	v_fma_f32 v30, -v7, v23, v157
	v_mul_f32_e32 v30, v30, v12
	v_rndne_f32_e32 v30, v30
	v_med3_f32 v30, v30, s33, v13
	v_cvt_i32_f32_e32 v23, v23
	v_cvt_i32_f32_e32 v30, v30
	v_and_b32_e32 v23, 15, v23
	v_and_b32_e32 v30, 15, v30
	v_lshl_or_b32 v211, v23, 20, v211
	v_lshl_or_b32 v215, v30, 20, v215
	v_mul_f32_e32 v21, v158, v11
	v_rndne_f32_e32 v21, v21
	v_med3_f32 v21, v21, s33, v13
	v_fma_f32 v22, -v7, v21, v158
	v_mul_f32_e32 v22, v22, v12
	v_rndne_f32_e32 v22, v22
	v_med3_f32 v22, v22, s33, v13
	v_cvt_i32_f32_e32 v21, v21
	v_cvt_i32_f32_e32 v22, v22
	v_and_b32_e32 v21, 15, v21
	v_and_b32_e32 v22, 15, v22
	v_lshl_or_b32 v211, v21, 24, v211
	v_lshl_or_b32 v215, v22, 24, v215
	v_mul_f32_e32 v23, v159, v11
	v_rndne_f32_e32 v23, v23
	v_med3_f32 v23, v23, s33, v13
	v_fma_f32 v30, -v7, v23, v159
	v_mul_f32_e32 v30, v30, v12
	v_rndne_f32_e32 v30, v30
	v_med3_f32 v30, v30, s33, v13
	v_cvt_i32_f32_e32 v23, v23
	v_cvt_i32_f32_e32 v30, v30
	v_lshl_or_b32 v211, v23, 28, v211
	v_lshl_or_b32 v215, v30, 28, v215
	s_waitcnt vmcnt(32)
	v_mul_f32_e32 v2, v24, v10
	v_mul_f32_e32 v236, v236, v2
	v_mul_f32_e32 v237, v237, v2
	v_mul_f32_e32 v238, v238, v234
	v_mul_f32_e32 v239, v239, v235
	ds_write_b32 v5, v236
	ds_write_b32 v5, v237 offset:256
	ds_write_b32 v5, v238 offset:512
	ds_write_b32 v5, v239 offset:768
	s_mov_b32 s86, 1
